# plus: w_out0^T touched by the idle helper workgroups at the end of P3 so that P5's B operand is cache-resident
# baseline (speedup 1.0000x reference)
.LBB0_237:
	v_lshlrev_b32_e32 v244, 4, v151
	s_sub_i32 s98, s92, 0x80
	s_lshl_b32 s98, s98, 17
	s_add_u32 s100, s50, 0x5800000
	s_addc_u32 s101, s51, 0
	s_add_u32 s100, s100, s98
	s_addc_u32 s101, s101, 0
	s_mov_b32 s99, 16
.Lwarm_wo0:
	global_load_dwordx4 v[240:243], v244, s[100:101]
	s_add_u32 s100, s100, 0x2000
	s_addc_u32 s101, s101, 0
	s_sub_u32 s99, s99, 1
	s_cmp_lg_u32 s99, 0
	s_cbranch_scc1 .Lwarm_wo0
	s_waitcnt vmcnt(0)
	s_mov_b64 s[16:17], 0
